# stick-breaking full-tile block: consecutive v_exp paired so 10 of the 15 s_nop pads behind transcendentals go away (order only); on top of the packed-to-scalar version
# baseline (speedup 1.0000x reference)
.LBB0_463:
	s_andn2_b64 vcc, exec, s[12:13]
	s_cbranch_vccnz .LBB0_465
	v_exp_f32_e32 v34, v117
	v_and_b32_e32 v39, 64, v238
	v_add_u32_e32 v39, 64, v39
	v_add_f32_e32 v35, 1.0, v34
	v_rcp_f32_e32 v36, v35
	v_exp_f32_e32 v35, v116
	v_exp_f32_e32 v40, v115
	v_add_f32_e32 v37, 1.0, v35
	v_rcp_f32_e32 v38, v37
	v_add_f32_e32 v37, 1.0, v40
	v_rcp_f32_e32 v42, v37
	v_exp_f32_e32 v41, v114
	v_exp_f32_e32 v44, v89
	v_add_f32_e32 v37, 1.0, v41
	v_rcp_f32_e32 v46, v37
	v_add_f32_e32 v37, 1.0, v44
	v_rcp_f32_e32 v48, v37
	v_exp_f32_e32 v45, v88
	v_exp_f32_e32 v86, v86
	v_add_f32_e32 v37, 1.0, v45
	v_rcp_f32_e32 v88, v37
	v_add_f32_e32 v37, 1.0, v86
	v_rcp_f32_e32 v49, v37
	v_exp_f32_e32 v87, v87
	s_nop 0
	v_add_f32_e32 v37, 1.0, v87
	v_rcp_f32_e32 v89, v37
	v_exp_f32_e32 v90, v90
	v_mul_f32_e32 v124, v48, v88
	v_mul_f32_e32 v125, v49, v89
	s_nop 0
	v_pk_mul_f32 v[124:125], v[124:125], v[124:125] op_sel:[0,1] op_sel_hi:[1,0]
	v_add_f32_e32 v37, 1.0, v90
	v_rcp_f32_e32 v114, v37
	v_exp_f32_e32 v91, v91
	v_exp_f32_e32 v118, v113
	v_add_f32_e32 v37, 1.0, v91
	v_rcp_f32_e32 v116, v37
	v_add_f32_e32 v37, 1.0, v118
	v_rcp_f32_e32 v115, v37
	v_exp_f32_e32 v119, v112
	s_nop 0
	v_add_f32_e32 v37, 1.0, v119
	v_rcp_f32_e32 v117, v37
	v_exp_f32_e32 v112, v111
	v_mul_f32_e32 v126, v114, v116
	v_mul_f32_e32 v127, v115, v117
	v_add_f32_e32 v37, 1.0, v112
	v_rcp_f32_e32 v120, v37
	v_exp_f32_e32 v113, v110
	v_exp_f32_e32 v122, v109
	v_add_f32_e32 v37, 1.0, v113
	v_rcp_f32_e32 v110, v37
	v_add_f32_e32 v37, 1.0, v122
	v_rcp_f32_e32 v121, v37
	v_exp_f32_e32 v123, v85
	s_nop 0
	v_add_f32_e32 v37, 1.0, v123
	v_rcp_f32_e32 v111, v37
	v_xor_b32_e32 v37, 32, v238
	v_cmp_lt_i32_e32 vcc, v37, v39
	s_nop 1
	v_cndmask_b32_e32 v37, v238, v37, vcc
	v_lshlrev_b32_e32 v85, 2, v37
	v_mul_f32_e32 v37, v126, v127
	v_mul_f32_e32 v126, v120, v110
	v_mul_f32_e32 v127, v121, v111
	ds_bpermute_b32 v43, v85, v37
	v_mul_f32_e32 v47, v126, v127
	ds_bpermute_b32 v109, v85, v47
	ds_bpermute_b32 v39, v85, v124
	s_waitcnt lgkmcnt(1)
	v_mul_f32_e32 v47, v47, v109
	v_mul_f32_e32 v125, v108, v109
	v_mul_f32_e32 v47, v108, v47
	v_cndmask_b32_e64 v126, v108, v125, s[10:11]
	v_mul_f32_e32 v108, v47, v43
	v_mul_f32_e32 v43, v37, v43
	v_mov_b32_e32 v37, v124
	v_cndmask_b32_e64 v127, v47, v108, s[10:11]
	v_mul_f32_e32 v108, v42, v46
	v_mul_f32_e32 v109, v43, v47
	s_waitcnt lgkmcnt(0)
	v_mul_f32_e32 v124, v36, v38
	v_mul_f32_e32 v125, v37, v39
	v_mul_f32_e32 v37, v109, v39
	v_mul_f32_e32 v124, v124, v108
	v_mul_f32_e32 v125, v125, v109
	ds_bpermute_b32 v85, v85, v124
	v_cndmask_b32_e64 v37, v109, v37, s[10:11]
	v_mul_f32_e32 v109, v111, v126
	v_mul_f32_e32 v108, v121, v109
	v_mul_f32_e32 v111, v110, v108
	s_waitcnt lgkmcnt(0)
	v_mul_f32_e32 v39, v125, v85
	v_cndmask_b32_e64 v39, v125, v39, s[10:11]
	v_mul_f32_e32 v121, v117, v127
	v_mul_f32_e32 v110, v120, v111
	v_mul_f32_e32 v120, v115, v121
	v_mul_f32_e32 v117, v89, v37
	v_mul_f32_e32 v43, v46, v39
	v_mul_f32_e32 v115, v116, v120
	v_mul_f32_e32 v116, v49, v117
	v_mul_f32_e32 v42, v42, v43
	v_mul_f32_e32 v89, v88, v116
	v_mul_f32_e32 v37, v38, v42
	v_mul_f32_e32 v114, v114, v115
	v_mul_f32_e32 v88, v48, v89
	v_mul_f32_e32 v36, v36, v37
	v_mul_f32_e32 v85, v124, v85
	v_mul_f32_e32 v48, v34, v36
	v_mul_f32_e32 v49, v35, v37
	v_mul_f32_e32 v46, v40, v42
	v_mul_f32_e32 v47, v41, v43
	v_mul_f32_e32 v44, v44, v88
	v_mul_f32_e32 v45, v45, v89
	v_mul_f32_e32 v40, v86, v116
	v_mul_f32_e32 v41, v87, v117
	v_mul_f32_e32 v38, v90, v114
	v_mul_f32_e32 v39, v91, v115
	v_mul_f32_e32 v34, v118, v120
	v_mul_f32_e32 v35, v119, v121
	v_mul_f32_e32 v42, v112, v110
	v_mul_f32_e32 v43, v113, v111
	v_mul_f32_e32 v36, v122, v108
	v_mul_f32_e32 v37, v123, v109
	v_mul_f32_e32 v118, v85, v125
